# GLU MIX stores write-through (sc1, 16-byte)
# baseline (speedup 1.0000x reference)
.LBB0_563:
	v_lshl_or_b32 v40, s62, 8, v227
	v_readlane_b32 s84, v254, 0
	v_ashrrev_i32_e32 v41, 31, v40
	v_readlane_b32 s88, v254, 4
	v_readlane_b32 s89, v254, 5
	v_lshl_add_u32 v200, s60, 8, v225
	v_ashrrev_i32_e32 v201, 31, v200
	v_lshl_add_u64 v[42:43], v[40:41], 2, s[88:89]
	global_load_dwordx4 v[60:63], v[42:43], off
	global_load_dwordx4 v[52:55], v[42:43], off offset:16
	global_load_dwordx4 v[44:47], v[42:43], off offset:512
	v_lshlrev_b64 v[198:199], 1, v[40:41]
	v_lshlrev_b64 v[40:41], 12, v[200:201]
	v_lshl_add_u64 v[202:203], s[8:9], 0, v[198:199]
	v_lshl_add_u64 v[204:205], s[6:7], 0, v[198:199]
	v_lshl_add_u64 v[144:145], v[202:203], 0, v[40:41]
	global_load_dwordx4 v[168:171], v[144:145], off
	v_lshl_add_u64 v[148:149], v[204:205], 0, v[40:41]
	global_load_dwordx4 v[172:175], v[148:149], off
	s_nop 0
	global_load_dwordx4 v[40:43], v[42:43], off offset:528
	v_or_b32_e32 v208, 16, v200
	global_load_dwordx4 v[156:159], v[144:145], off offset:256
	global_load_dwordx4 v[152:155], v[148:149], off offset:256
	v_ashrrev_i32_e32 v209, 31, v208
	v_lshlrev_b64 v[146:147], 13, v[200:201]
	v_lshlrev_b64 v[144:145], 12, v[208:209]
	v_lshl_add_u64 v[146:147], s[56:57], 0, v[146:147]
	v_lshl_add_u64 v[148:149], v[202:203], 0, v[144:145]
	v_lshl_add_u64 v[150:151], v[204:205], 0, v[144:145]
	v_lshl_add_u64 v[206:207], v[146:147], 0, v[198:199]
	global_load_dwordx4 v[164:167], v[148:149], off
	global_load_dwordx4 v[144:147], v[148:149], off offset:256
	global_load_dwordx4 v[160:163], v[150:151], off
	s_nop 0
	global_load_dwordx4 v[148:151], v[150:151], off offset:256
	v_add_co_u32_e32 v206, vcc, s81, v206
	v_readlane_b32 s85, v254, 1
	s_nop 0
	v_addc_co_u32_e32 v207, vcc, 0, v207, vcc
	v_readlane_b32 s86, v254, 2
	v_readlane_b32 s87, v254, 3
	v_readlane_b32 s90, v254, 6
	v_readlane_b32 s91, v254, 7
	s_waitcnt vmcnt(0)
	v_pk_add_f32 v[140:141], v[140:141], v[60:61]
	v_pk_add_f32 v[142:143], v[142:143], v[62:63]
	v_pk_add_f32 v[138:139], v[138:139], v[54:55]
	v_pk_add_f32 v[232:233], v[134:135], v[46:47]
	v_pk_mul_f32 v[134:135], v[140:141], s[36:37] op_sel_hi:[1,0]
	v_pk_add_f32 v[136:137], v[136:137], v[52:53]
	v_pk_mul_f32 v[140:141], v[142:143], s[36:37] op_sel_hi:[1,0]
	v_pk_mul_f32 v[138:139], v[138:139], s[36:37] op_sel_hi:[1,0]
	v_exp_f32_e32 v134, v134
	v_exp_f32_e32 v135, v135
	v_pk_mul_f32 v[136:137], v[136:137], s[36:37] op_sel_hi:[1,0]
	v_exp_f32_e32 v140, v140
	v_exp_f32_e32 v141, v141
	v_exp_f32_e32 v138, v138
	v_exp_f32_e32 v139, v139
	v_exp_f32_e32 v136, v136
	v_exp_f32_e32 v137, v137
	v_pk_add_f32 v[134:135], v[134:135], 1.0 op_sel_hi:[1,0]
	v_pk_add_f32 v[132:133], v[132:133], v[44:45]
	v_pk_add_f32 v[140:141], v[140:141], 1.0 op_sel_hi:[1,0]
	v_pk_add_f32 v[138:139], v[138:139], 1.0 op_sel_hi:[1,0]
	v_rcp_f32_e32 v134, v134
	v_rcp_f32_e32 v135, v135
	v_pk_mul_f32 v[132:133], v[132:133], s[36:37] op_sel_hi:[1,0]
	v_pk_add_f32 v[136:137], v[136:137], 1.0 op_sel_hi:[1,0]
	v_rcp_f32_e32 v140, v140
	v_rcp_f32_e32 v141, v141
	v_rcp_f32_e32 v138, v138
	v_rcp_f32_e32 v139, v139
	v_lshlrev_b32_e32 v142, 16, v168
	v_and_b32_e32 v143, 0xffff0000, v168
	v_lshlrev_b32_e32 v234, 16, v172
	v_and_b32_e32 v235, 0xffff0000, v172
	v_exp_f32_e32 v240, v132
	v_exp_f32_e32 v241, v133
	v_rcp_f32_e32 v136, v136
	v_rcp_f32_e32 v137, v137
	v_lshlrev_b32_e32 v168, 16, v169
	v_and_b32_e32 v169, 0xffff0000, v169
	v_lshlrev_b32_e32 v172, 16, v173
	v_and_b32_e32 v173, 0xffff0000, v173
	v_lshlrev_b32_e32 v236, 16, v170
	v_and_b32_e32 v237, 0xffff0000, v170
	v_lshlrev_b32_e32 v238, 16, v174
	v_and_b32_e32 v239, 0xffff0000, v174
	v_lshlrev_b32_e32 v170, 16, v171
	v_and_b32_e32 v171, 0xffff0000, v171
	v_lshlrev_b32_e32 v174, 16, v175
	v_and_b32_e32 v175, 0xffff0000, v175
	v_pk_mul_f32 v[132:133], v[142:143], v[234:235]
	v_pk_mul_f32 v[142:143], v[168:169], v[172:173]
	v_pk_mul_f32 v[170:171], v[170:171], v[174:175]
	v_pk_mul_f32 v[132:133], v[132:133], v[134:135]
	v_pk_mul_f32 v[168:169], v[236:237], v[238:239]
	v_pk_mul_f32 v[134:135], v[142:143], v[140:141]
	v_pk_mul_f32 v[138:139], v[170:171], v[138:139]
	v_cvt_pk_bf16_f32 v132, v132, v133
	v_cvt_pk_bf16_f32 v133, v134, v135
	v_pk_mul_f32 v[136:137], v[168:169], v[136:137]
	v_cvt_pk_bf16_f32 v135, v138, v139
	v_pk_mul_f32 v[138:139], v[232:233], s[36:37] op_sel_hi:[1,0]
	v_cvt_pk_bf16_f32 v134, v136, v137
	global_store_dwordx4 v[206:207], v[132:135], off sc1
	v_exp_f32_e32 v138, v138
	v_exp_f32_e32 v139, v139
	v_pk_add_f32 v[132:133], v[240:241], 1.0 op_sel_hi:[1,0]
	v_pk_add_f32 v[128:129], v[128:129], v[40:41]
	v_rcp_f32_e32 v132, v132
	v_rcp_f32_e32 v133, v133
	v_pk_mul_f32 v[128:129], v[128:129], s[36:37] op_sel_hi:[1,0]
	v_lshlrev_b32_e32 v134, 16, v156
	v_and_b32_e32 v135, 0xffff0000, v156
	v_lshlrev_b32_e32 v136, 16, v152
	v_and_b32_e32 v137, 0xffff0000, v152
	v_exp_f32_e32 v128, v128
	v_exp_f32_e32 v129, v129
	v_pk_mul_f32 v[134:135], v[134:135], v[136:137]
	v_pk_add_f32 v[130:131], v[130:131], v[42:43]
	v_pk_mul_f32 v[132:133], v[134:135], v[132:133]
	v_pk_add_f32 v[134:135], v[138:139], 1.0 op_sel_hi:[1,0]
	v_pk_add_f32 v[128:129], v[128:129], 1.0 op_sel_hi:[1,0]
	v_rcp_f32_e32 v134, v134
	v_rcp_f32_e32 v135, v135
	v_pk_mul_f32 v[130:131], v[130:131], s[36:37] op_sel_hi:[1,0]
	v_lshlrev_b32_e32 v136, 16, v157
	v_and_b32_e32 v137, 0xffff0000, v157
	v_lshlrev_b32_e32 v138, 16, v153
	v_and_b32_e32 v139, 0xffff0000, v153
	v_rcp_f32_e32 v128, v128
	v_rcp_f32_e32 v129, v129
	v_exp_f32_e32 v130, v130
	v_exp_f32_e32 v131, v131
	v_pk_add_f32 v[124:125], v[124:125], v[60:61]
	v_pk_mul_f32 v[136:137], v[136:137], v[138:139]
	v_pk_mul_f32 v[124:125], v[124:125], s[36:37] op_sel_hi:[1,0]
	v_pk_mul_f32 v[134:135], v[136:137], v[134:135]
	v_lshlrev_b32_e32 v136, 16, v158
	v_and_b32_e32 v137, 0xffff0000, v158
	v_lshlrev_b32_e32 v138, 16, v154
	v_and_b32_e32 v139, 0xffff0000, v154
	v_exp_f32_e32 v124, v124
	v_exp_f32_e32 v125, v125
	v_pk_add_f32 v[126:127], v[126:127], v[62:63]
	v_pk_mul_f32 v[136:137], v[136:137], v[138:139]
	v_pk_mul_f32 v[126:127], v[126:127], s[36:37] op_sel_hi:[1,0]
	v_pk_mul_f32 v[136:137], v[136:137], v[128:129]
	v_pk_add_f32 v[128:129], v[130:131], 1.0 op_sel_hi:[1,0]
	v_exp_f32_e32 v126, v126
	v_exp_f32_e32 v127, v127
	v_pk_add_f32 v[120:121], v[120:121], v[52:53]
	v_rcp_f32_e32 v128, v128
	v_rcp_f32_e32 v129, v129
	v_pk_mul_f32 v[120:121], v[120:121], s[36:37] op_sel_hi:[1,0]
	v_pk_add_f32 v[124:125], v[124:125], 1.0 op_sel_hi:[1,0]
	v_exp_f32_e32 v120, v120
	v_exp_f32_e32 v121, v121
	v_pk_add_f32 v[122:123], v[122:123], v[54:55]
	v_lshlrev_b32_e32 v130, 16, v159
	v_and_b32_e32 v131, 0xffff0000, v159
	v_lshlrev_b32_e32 v138, 16, v155
	v_and_b32_e32 v139, 0xffff0000, v155
	v_rcp_f32_e32 v124, v124
	v_rcp_f32_e32 v125, v125
	v_pk_mul_f32 v[122:123], v[122:123], s[36:37] op_sel_hi:[1,0]
	v_pk_mul_f32 v[130:131], v[130:131], v[138:139]
	v_pk_add_f32 v[126:127], v[126:127], 1.0 op_sel_hi:[1,0]
	v_exp_f32_e32 v122, v122
	v_exp_f32_e32 v123, v123
	v_pk_mul_f32 v[140:141], v[130:131], v[128:129]
	v_cvt_pk_bf16_f32 v129, v134, v135
	v_cvt_pk_bf16_f32 v130, v136, v137
	v_lshlrev_b32_e32 v134, 16, v164
	v_and_b32_e32 v135, 0xffff0000, v164
	v_lshlrev_b32_e32 v136, 16, v160
	v_and_b32_e32 v137, 0xffff0000, v160
	v_rcp_f32_e32 v126, v126
	v_rcp_f32_e32 v127, v127
	v_pk_mul_f32 v[134:135], v[134:135], v[136:137]
	v_pk_add_f32 v[120:121], v[120:121], 1.0 op_sel_hi:[1,0]
	v_pk_mul_f32 v[124:125], v[124:125], v[134:135]
	v_lshlrev_b32_e32 v134, 16, v165
	v_and_b32_e32 v135, 0xffff0000, v165
	v_lshlrev_b32_e32 v136, 16, v161
	v_and_b32_e32 v137, 0xffff0000, v161
	v_rcp_f32_e32 v120, v120
	v_rcp_f32_e32 v121, v121
	v_pk_mul_f32 v[134:135], v[134:135], v[136:137]
	v_pk_add_f32 v[122:123], v[122:123], 1.0 op_sel_hi:[1,0]
	v_pk_mul_f32 v[126:127], v[126:127], v[134:135]
	v_lshlrev_b32_e32 v134, 16, v166
	v_and_b32_e32 v135, 0xffff0000, v166
	v_lshlrev_b32_e32 v136, 16, v162
	v_and_b32_e32 v137, 0xffff0000, v162
	v_rcp_f32_e32 v122, v122
	v_rcp_f32_e32 v123, v123
	v_pk_mul_f32 v[134:135], v[134:135], v[136:137]
	v_lshlrev_b32_e32 v136, 16, v163
	v_pk_mul_f32 v[120:121], v[120:121], v[134:135]
	v_lshlrev_b32_e32 v134, 16, v167
	v_and_b32_e32 v135, 0xffff0000, v167
	v_and_b32_e32 v137, 0xffff0000, v163
	v_pk_add_f32 v[116:117], v[116:117], v[44:45]
	v_cvt_pk_bf16_f32 v128, v132, v133
	v_lshlrev_b64 v[132:133], 13, v[208:209]
	v_pk_mul_f32 v[134:135], v[134:135], v[136:137]
	v_pk_mul_f32 v[116:117], v[116:117], s[36:37] op_sel_hi:[1,0]
	v_pk_mul_f32 v[134:135], v[122:123], v[134:135]
	v_cvt_pk_bf16_f32 v122, v124, v125
	v_cvt_pk_bf16_f32 v124, v120, v121
	v_lshl_add_u64 v[120:121], s[56:57], 0, v[132:133]
	v_exp_f32_e32 v116, v116
	v_exp_f32_e32 v117, v117
	v_pk_add_f32 v[118:119], v[118:119], v[46:47]
	v_lshl_add_u64 v[120:121], v[120:121], 0, v[198:199]
	v_pk_mul_f32 v[118:119], v[118:119], s[36:37] op_sel_hi:[1,0]
	v_add_co_u32_e32 v120, vcc, s81, v120
	v_or_b32_e32 v152, 32, v200
	v_exp_f32_e32 v118, v118
	v_exp_f32_e32 v119, v119
	v_pk_add_f32 v[112:113], v[112:113], v[40:41]
	v_cvt_pk_bf16_f32 v123, v126, v127
	v_addc_co_u32_e32 v121, vcc, 0, v121, vcc
	v_ashrrev_i32_e32 v153, 31, v152
	v_pk_mul_f32 v[112:113], v[112:113], s[36:37] op_sel_hi:[1,0]
	v_cvt_pk_bf16_f32 v125, v134, v135
	global_store_dwordx4 v[120:121], v[122:125], off sc1
	v_pk_add_f32 v[116:117], v[116:117], 1.0 op_sel_hi:[1,0]
	v_exp_f32_e32 v112, v112
	v_lshlrev_b64 v[122:123], 12, v[152:153]
	v_exp_f32_e32 v113, v113
	v_lshl_add_u64 v[124:125], v[202:203], 0, v[122:123]
	v_lshl_add_u64 v[122:123], v[204:205], 0, v[122:123]
	v_rcp_f32_e32 v116, v116
	v_rcp_f32_e32 v117, v117
	global_load_dwordx4 v[132:135], v[124:125], off
	global_load_dwordx4 v[136:139], v[122:123], off
	v_pk_add_f32 v[118:119], v[118:119], 1.0 op_sel_hi:[1,0]
	v_cvt_pk_bf16_f32 v131, v140, v141
	global_store_dwordx4 v[206:207], v[128:131], off offset:256 sc1
	v_lshlrev_b32_e32 v126, 16, v144
	v_and_b32_e32 v127, 0xffff0000, v144
	v_lshlrev_b32_e32 v128, 16, v148
	v_and_b32_e32 v129, 0xffff0000, v148
	v_rcp_f32_e32 v118, v118
	v_rcp_f32_e32 v119, v119
	v_pk_add_f32 v[114:115], v[114:115], v[42:43]
	v_pk_mul_f32 v[126:127], v[126:127], v[128:129]
	v_pk_add_f32 v[112:113], v[112:113], 1.0 op_sel_hi:[1,0]
	v_pk_mul_f32 v[114:115], v[114:115], s[36:37] op_sel_hi:[1,0]
	v_pk_mul_f32 v[116:117], v[116:117], v[126:127]
	v_lshlrev_b32_e32 v126, 16, v145
	v_and_b32_e32 v127, 0xffff0000, v145
	v_lshlrev_b32_e32 v128, 16, v149
	v_and_b32_e32 v129, 0xffff0000, v149
	v_rcp_f32_e32 v112, v112
	v_rcp_f32_e32 v113, v113
	v_exp_f32_e32 v114, v114
	v_exp_f32_e32 v115, v115
	v_pk_mul_f32 v[126:127], v[126:127], v[128:129]
	v_lshlrev_b32_e32 v128, 16, v150
	v_pk_mul_f32 v[118:119], v[118:119], v[126:127]
	v_lshlrev_b32_e32 v126, 16, v146
	v_and_b32_e32 v127, 0xffff0000, v146
	v_and_b32_e32 v129, 0xffff0000, v150
	v_pk_mul_f32 v[126:127], v[126:127], v[128:129]
	v_lshlrev_b32_e32 v128, 16, v151
	v_pk_mul_f32 v[126:127], v[112:113], v[126:127]
	v_pk_add_f32 v[112:113], v[114:115], 1.0 op_sel_hi:[1,0]
	v_lshlrev_b32_e32 v114, 16, v147
	v_rcp_f32_e32 v112, v112
	v_rcp_f32_e32 v113, v113
	v_and_b32_e32 v115, 0xffff0000, v147
	v_and_b32_e32 v129, 0xffff0000, v151
	v_pk_mul_f32 v[114:115], v[114:115], v[128:129]
	v_or_b32_e32 v144, 48, v200
	v_pk_mul_f32 v[128:129], v[112:113], v[114:115]
	v_cvt_pk_bf16_f32 v112, v116, v117
	v_cvt_pk_bf16_f32 v113, v118, v119
	v_cvt_pk_bf16_f32 v114, v126, v127
	v_ashrrev_i32_e32 v145, 31, v144
	v_cvt_pk_bf16_f32 v115, v128, v129
	global_store_dwordx4 v[120:121], v[112:115], off offset:256 sc1
	global_load_dwordx4 v[140:143], v[124:125], off offset:256
	global_load_dwordx4 v[128:131], v[122:123], off offset:256
	v_lshlrev_b64 v[112:113], 12, v[144:145]
	v_lshl_add_u64 v[114:115], v[202:203], 0, v[112:113]
	v_lshl_add_u64 v[116:117], v[204:205], 0, v[112:113]
	global_load_dwordx4 v[120:123], v[114:115], off
	s_nop 0
	global_load_dwordx4 v[112:115], v[114:115], off offset:256
	s_nop 0
	global_load_dwordx4 v[124:127], v[116:117], off
	s_nop 0
	global_load_dwordx4 v[116:119], v[116:117], off offset:256
	v_pk_add_f32 v[110:111], v[110:111], v[62:63]
	v_pk_add_f32 v[104:105], v[104:105], v[52:53]
	v_pk_mul_f32 v[110:111], v[110:111], s[36:37] op_sel_hi:[1,0]
	v_pk_mul_f32 v[104:105], v[104:105], s[36:37] op_sel_hi:[1,0]
	v_exp_f32_e32 v110, v110
	v_exp_f32_e32 v111, v111
	v_exp_f32_e32 v104, v104
	v_exp_f32_e32 v105, v105
	v_pk_add_f32 v[108:109], v[108:109], v[60:61]
	v_pk_add_f32 v[110:111], v[110:111], 1.0 op_sel_hi:[1,0]
	v_pk_mul_f32 v[108:109], v[108:109], s[36:37] op_sel_hi:[1,0]
	v_rcp_f32_e32 v110, v110
	v_rcp_f32_e32 v111, v111
	v_pk_add_f32 v[106:107], v[106:107], v[54:55]
	v_exp_f32_e32 v108, v108
	v_exp_f32_e32 v109, v109
	v_pk_add_f32 v[104:105], v[104:105], 1.0 op_sel_hi:[1,0]
	v_pk_mul_f32 v[106:107], v[106:107], s[36:37] op_sel_hi:[1,0]
	v_rcp_f32_e32 v104, v104
	v_rcp_f32_e32 v105, v105
	v_exp_f32_e32 v106, v106
	v_exp_f32_e32 v107, v107
	v_pk_add_f32 v[108:109], v[108:109], 1.0 op_sel_hi:[1,0]
	v_pk_add_f32 v[100:101], v[100:101], v[44:45]
	v_rcp_f32_e32 v108, v108
	v_rcp_f32_e32 v109, v109
	s_waitcnt vmcnt(0)
	v_lshlrev_b32_e32 v148, 16, v132
	v_and_b32_e32 v149, 0xffff0000, v132
	v_lshlrev_b32_e32 v150, 16, v136
	v_and_b32_e32 v151, 0xffff0000, v136
	v_lshlrev_b32_e32 v132, 16, v133
	v_and_b32_e32 v133, 0xffff0000, v133
	v_lshlrev_b32_e32 v136, 16, v137
	v_and_b32_e32 v137, 0xffff0000, v137
	v_pk_mul_f32 v[132:133], v[132:133], v[136:137]
	v_lshlrev_b32_e32 v136, 16, v138
	v_pk_mul_f32 v[110:111], v[110:111], v[132:133]
	v_lshlrev_b32_e32 v132, 16, v134
	v_and_b32_e32 v133, 0xffff0000, v134
	v_and_b32_e32 v137, 0xffff0000, v138
	v_pk_mul_f32 v[132:133], v[132:133], v[136:137]
	v_pk_mul_f32 v[100:101], v[100:101], s[36:37] op_sel_hi:[1,0]
	v_pk_mul_f32 v[132:133], v[104:105], v[132:133]
	v_pk_add_f32 v[104:105], v[106:107], 1.0 op_sel_hi:[1,0]
	v_exp_f32_e32 v100, v100
	v_rcp_f32_e32 v104, v104
	v_rcp_f32_e32 v105, v105
	v_exp_f32_e32 v101, v101
	v_pk_add_f32 v[102:103], v[102:103], v[46:47]
	v_pk_mul_f32 v[148:149], v[148:149], v[150:151]
	v_lshlrev_b32_e32 v106, 16, v135
	v_and_b32_e32 v107, 0xffff0000, v135
	v_lshlrev_b32_e32 v134, 16, v139
	v_and_b32_e32 v135, 0xffff0000, v139
	v_pk_mul_f32 v[102:103], v[102:103], s[36:37] op_sel_hi:[1,0]
	v_lshlrev_b64 v[146:147], 13, v[152:153]
	v_pk_mul_f32 v[108:109], v[108:109], v[148:149]
	v_pk_mul_f32 v[106:107], v[106:107], v[134:135]
	v_exp_f32_e32 v102, v102
	v_exp_f32_e32 v103, v103
	v_pk_add_f32 v[96:97], v[96:97], v[40:41]
	v_pk_mul_f32 v[134:135], v[104:105], v[106:107]
	v_cvt_pk_bf16_f32 v104, v108, v109
	v_lshl_add_u64 v[108:109], s[56:57], 0, v[146:147]
	v_pk_mul_f32 v[96:97], v[96:97], s[36:37] op_sel_hi:[1,0]
	v_lshl_add_u64 v[108:109], v[108:109], 0, v[198:199]
	v_pk_add_f32 v[100:101], v[100:101], 1.0 op_sel_hi:[1,0]
	v_exp_f32_e32 v96, v96
	v_exp_f32_e32 v97, v97
	v_add_co_u32_e32 v108, vcc, s81, v108
	v_rcp_f32_e32 v100, v100
	v_rcp_f32_e32 v101, v101
	v_cvt_pk_bf16_f32 v105, v110, v111
	v_cvt_pk_bf16_f32 v106, v132, v133
	v_cvt_pk_bf16_f32 v107, v134, v135
	v_addc_co_u32_e32 v109, vcc, 0, v109, vcc
	v_pk_add_f32 v[102:103], v[102:103], 1.0 op_sel_hi:[1,0]
	global_store_dwordx4 v[108:109], v[104:107], off sc1
	v_rcp_f32_e32 v102, v102
	v_rcp_f32_e32 v103, v103
	v_lshlrev_b32_e32 v104, 16, v140
	v_and_b32_e32 v105, 0xffff0000, v140
	v_lshlrev_b32_e32 v106, 16, v128
	v_and_b32_e32 v107, 0xffff0000, v128
	v_pk_add_f32 v[98:99], v[98:99], v[42:43]
	v_pk_mul_f32 v[104:105], v[104:105], v[106:107]
	v_pk_add_f32 v[96:97], v[96:97], 1.0 op_sel_hi:[1,0]
	v_pk_mul_f32 v[98:99], v[98:99], s[36:37] op_sel_hi:[1,0]
	v_pk_mul_f32 v[100:101], v[100:101], v[104:105]
	v_lshlrev_b32_e32 v104, 16, v141
	v_and_b32_e32 v105, 0xffff0000, v141
	v_lshlrev_b32_e32 v106, 16, v129
	v_and_b32_e32 v107, 0xffff0000, v129
	v_rcp_f32_e32 v96, v96
	v_rcp_f32_e32 v97, v97
	v_exp_f32_e32 v98, v98
	v_exp_f32_e32 v99, v99
	v_pk_add_f32 v[92:93], v[92:93], v[60:61]
	v_pk_mul_f32 v[104:105], v[104:105], v[106:107]
	v_pk_mul_f32 v[92:93], v[92:93], s[36:37] op_sel_hi:[1,0]
	v_pk_mul_f32 v[102:103], v[102:103], v[104:105]
	v_lshlrev_b32_e32 v104, 16, v142
	v_and_b32_e32 v105, 0xffff0000, v142
	v_lshlrev_b32_e32 v106, 16, v130
	v_and_b32_e32 v107, 0xffff0000, v130
	v_exp_f32_e32 v92, v92
	v_exp_f32_e32 v93, v93
	v_pk_add_f32 v[94:95], v[94:95], v[62:63]
	v_pk_mul_f32 v[104:105], v[104:105], v[106:107]
	v_pk_mul_f32 v[94:95], v[94:95], s[36:37] op_sel_hi:[1,0]
	v_pk_mul_f32 v[104:105], v[96:97], v[104:105]
	v_pk_add_f32 v[96:97], v[98:99], 1.0 op_sel_hi:[1,0]
	v_exp_f32_e32 v94, v94
	v_exp_f32_e32 v95, v95
	v_pk_add_f32 v[88:89], v[88:89], v[52:53]
	v_rcp_f32_e32 v96, v96
	v_rcp_f32_e32 v97, v97
	v_pk_mul_f32 v[88:89], v[88:89], s[36:37] op_sel_hi:[1,0]
	v_pk_add_f32 v[92:93], v[92:93], 1.0 op_sel_hi:[1,0]
	v_exp_f32_e32 v88, v88
	v_exp_f32_e32 v89, v89
	v_pk_add_f32 v[90:91], v[90:91], v[54:55]
	v_lshlrev_b32_e32 v98, 16, v143
	v_and_b32_e32 v99, 0xffff0000, v143
	v_lshlrev_b32_e32 v106, 16, v131
	v_and_b32_e32 v107, 0xffff0000, v131
	v_rcp_f32_e32 v92, v92
	v_rcp_f32_e32 v93, v93
	v_pk_mul_f32 v[90:91], v[90:91], s[36:37] op_sel_hi:[1,0]
	v_pk_mul_f32 v[98:99], v[98:99], v[106:107]
	v_pk_add_f32 v[94:95], v[94:95], 1.0 op_sel_hi:[1,0]
	v_exp_f32_e32 v90, v90
	v_exp_f32_e32 v91, v91
	v_pk_mul_f32 v[110:111], v[96:97], v[98:99]
	v_cvt_pk_bf16_f32 v97, v102, v103
	v_cvt_pk_bf16_f32 v98, v104, v105
	v_lshlrev_b32_e32 v102, 16, v120
	v_and_b32_e32 v103, 0xffff0000, v120
	v_lshlrev_b32_e32 v104, 16, v124
	v_and_b32_e32 v105, 0xffff0000, v124
	v_rcp_f32_e32 v94, v94
	v_rcp_f32_e32 v95, v95
	v_pk_mul_f32 v[102:103], v[102:103], v[104:105]
	v_pk_add_f32 v[88:89], v[88:89], 1.0 op_sel_hi:[1,0]
	v_pk_mul_f32 v[92:93], v[92:93], v[102:103]
	v_lshlrev_b32_e32 v102, 16, v121
	v_and_b32_e32 v103, 0xffff0000, v121
	v_lshlrev_b32_e32 v104, 16, v125
	v_and_b32_e32 v105, 0xffff0000, v125
	v_rcp_f32_e32 v88, v88
	v_rcp_f32_e32 v89, v89
	v_pk_mul_f32 v[102:103], v[102:103], v[104:105]
	v_pk_add_f32 v[90:91], v[90:91], 1.0 op_sel_hi:[1,0]
	v_pk_mul_f32 v[94:95], v[94:95], v[102:103]
	v_lshlrev_b32_e32 v102, 16, v122
	v_and_b32_e32 v103, 0xffff0000, v122
	v_lshlrev_b32_e32 v104, 16, v126
	v_and_b32_e32 v105, 0xffff0000, v126
	v_rcp_f32_e32 v90, v90
	v_rcp_f32_e32 v91, v91
	v_pk_mul_f32 v[102:103], v[102:103], v[104:105]
	v_lshlrev_b32_e32 v104, 16, v127
	v_pk_mul_f32 v[88:89], v[88:89], v[102:103]
	v_lshlrev_b32_e32 v102, 16, v123
	v_and_b32_e32 v103, 0xffff0000, v123
	v_and_b32_e32 v105, 0xffff0000, v127
	v_pk_add_f32 v[84:85], v[84:85], v[44:45]
	v_cvt_pk_bf16_f32 v96, v100, v101
	v_lshlrev_b64 v[100:101], 13, v[144:145]
	v_pk_mul_f32 v[102:103], v[102:103], v[104:105]
	v_pk_mul_f32 v[84:85], v[84:85], s[36:37] op_sel_hi:[1,0]
	v_pk_mul_f32 v[102:103], v[90:91], v[102:103]
	v_cvt_pk_bf16_f32 v90, v92, v93
	v_cvt_pk_bf16_f32 v92, v88, v89
	v_lshl_add_u64 v[88:89], s[56:57], 0, v[100:101]
	v_exp_f32_e32 v84, v84
	v_exp_f32_e32 v85, v85
	v_pk_add_f32 v[86:87], v[86:87], v[46:47]
	v_lshl_add_u64 v[88:89], v[88:89], 0, v[198:199]
	v_pk_mul_f32 v[86:87], v[86:87], s[36:37] op_sel_hi:[1,0]
	v_add_co_u32_e32 v88, vcc, s81, v88
	v_add_u32_e32 v120, 0x80, v200
	v_exp_f32_e32 v86, v86
	v_exp_f32_e32 v87, v87
	v_pk_add_f32 v[80:81], v[80:81], v[40:41]
	v_cvt_pk_bf16_f32 v91, v94, v95
	v_addc_co_u32_e32 v89, vcc, 0, v89, vcc
	v_ashrrev_i32_e32 v121, 31, v120
	v_pk_mul_f32 v[80:81], v[80:81], s[36:37] op_sel_hi:[1,0]
	v_cvt_pk_bf16_f32 v93, v102, v103
	global_store_dwordx4 v[88:89], v[90:93], off sc1
	v_pk_add_f32 v[84:85], v[84:85], 1.0 op_sel_hi:[1,0]
	v_exp_f32_e32 v80, v80
	v_lshlrev_b64 v[90:91], 12, v[120:121]
	v_exp_f32_e32 v81, v81
	v_lshl_add_u64 v[92:93], v[202:203], 0, v[90:91]
	v_lshl_add_u64 v[90:91], v[204:205], 0, v[90:91]
	v_rcp_f32_e32 v84, v84
	v_rcp_f32_e32 v85, v85
	global_load_dwordx4 v[100:103], v[92:93], off
	global_load_dwordx4 v[104:107], v[90:91], off
	v_pk_add_f32 v[86:87], v[86:87], 1.0 op_sel_hi:[1,0]
	v_cvt_pk_bf16_f32 v99, v110, v111
	global_store_dwordx4 v[108:109], v[96:99], off offset:256 sc1
	v_lshlrev_b32_e32 v94, 16, v112
	v_and_b32_e32 v95, 0xffff0000, v112
	v_lshlrev_b32_e32 v96, 16, v116
	v_and_b32_e32 v97, 0xffff0000, v116
	v_rcp_f32_e32 v86, v86
	v_rcp_f32_e32 v87, v87
	v_pk_add_f32 v[82:83], v[82:83], v[42:43]
	v_pk_mul_f32 v[94:95], v[94:95], v[96:97]
	v_pk_add_f32 v[80:81], v[80:81], 1.0 op_sel_hi:[1,0]
	v_pk_mul_f32 v[82:83], v[82:83], s[36:37] op_sel_hi:[1,0]
	v_pk_mul_f32 v[84:85], v[84:85], v[94:95]
	v_lshlrev_b32_e32 v94, 16, v113
	v_and_b32_e32 v95, 0xffff0000, v113
	v_lshlrev_b32_e32 v96, 16, v117
	v_and_b32_e32 v97, 0xffff0000, v117
	v_rcp_f32_e32 v80, v80
	v_rcp_f32_e32 v81, v81
	v_exp_f32_e32 v82, v82
	v_exp_f32_e32 v83, v83
	v_pk_mul_f32 v[94:95], v[94:95], v[96:97]
	v_lshlrev_b32_e32 v96, 16, v118
	v_pk_mul_f32 v[86:87], v[86:87], v[94:95]
	v_lshlrev_b32_e32 v94, 16, v114
	v_and_b32_e32 v95, 0xffff0000, v114
	v_and_b32_e32 v97, 0xffff0000, v118
	v_pk_mul_f32 v[94:95], v[94:95], v[96:97]
	v_lshlrev_b32_e32 v96, 16, v119
	v_pk_mul_f32 v[94:95], v[80:81], v[94:95]
	v_pk_add_f32 v[80:81], v[82:83], 1.0 op_sel_hi:[1,0]
	v_lshlrev_b32_e32 v82, 16, v115
	v_rcp_f32_e32 v80, v80
	v_rcp_f32_e32 v81, v81
	v_and_b32_e32 v83, 0xffff0000, v115
	v_and_b32_e32 v97, 0xffff0000, v119
	v_pk_mul_f32 v[82:83], v[82:83], v[96:97]
	v_add_u32_e32 v112, 0x90, v200
	v_pk_mul_f32 v[96:97], v[80:81], v[82:83]
	v_cvt_pk_bf16_f32 v80, v84, v85
	v_cvt_pk_bf16_f32 v81, v86, v87
	v_cvt_pk_bf16_f32 v82, v94, v95
	v_ashrrev_i32_e32 v113, 31, v112
	v_cvt_pk_bf16_f32 v83, v96, v97
	global_store_dwordx4 v[88:89], v[80:83], off offset:256 sc1
	global_load_dwordx4 v[108:111], v[92:93], off offset:256
	global_load_dwordx4 v[96:99], v[90:91], off offset:256
	v_lshlrev_b64 v[80:81], 12, v[112:113]
	v_lshl_add_u64 v[82:83], v[202:203], 0, v[80:81]
	v_lshl_add_u64 v[84:85], v[204:205], 0, v[80:81]
	global_load_dwordx4 v[88:91], v[82:83], off
	s_nop 0
	global_load_dwordx4 v[80:83], v[82:83], off offset:256
	s_nop 0
	global_load_dwordx4 v[92:95], v[84:85], off
	s_nop 0
	global_load_dwordx4 v[84:87], v[84:85], off offset:256
	v_pk_add_f32 v[78:79], v[78:79], v[62:63]
	v_pk_add_f32 v[72:73], v[72:73], v[52:53]
	v_pk_mul_f32 v[78:79], v[78:79], s[36:37] op_sel_hi:[1,0]
	v_pk_mul_f32 v[72:73], v[72:73], s[36:37] op_sel_hi:[1,0]
	v_exp_f32_e32 v78, v78
	v_exp_f32_e32 v79, v79
	v_exp_f32_e32 v72, v72
	v_exp_f32_e32 v73, v73
	v_pk_add_f32 v[76:77], v[76:77], v[60:61]
	v_pk_add_f32 v[78:79], v[78:79], 1.0 op_sel_hi:[1,0]
	v_pk_mul_f32 v[76:77], v[76:77], s[36:37] op_sel_hi:[1,0]
	v_rcp_f32_e32 v78, v78
	v_rcp_f32_e32 v79, v79
	v_pk_add_f32 v[74:75], v[74:75], v[54:55]
	v_exp_f32_e32 v76, v76
	v_exp_f32_e32 v77, v77
	v_pk_add_f32 v[72:73], v[72:73], 1.0 op_sel_hi:[1,0]
	v_pk_mul_f32 v[74:75], v[74:75], s[36:37] op_sel_hi:[1,0]
	v_rcp_f32_e32 v72, v72
	v_rcp_f32_e32 v73, v73
	v_exp_f32_e32 v74, v74
	v_exp_f32_e32 v75, v75
	v_pk_add_f32 v[76:77], v[76:77], 1.0 op_sel_hi:[1,0]
	v_pk_add_f32 v[68:69], v[68:69], v[44:45]
	v_rcp_f32_e32 v76, v76
	v_rcp_f32_e32 v77, v77
	s_waitcnt vmcnt(0)
	v_lshlrev_b32_e32 v116, 16, v100
	v_and_b32_e32 v117, 0xffff0000, v100
	v_lshlrev_b32_e32 v118, 16, v104
	v_and_b32_e32 v119, 0xffff0000, v104
	v_lshlrev_b32_e32 v100, 16, v101
	v_and_b32_e32 v101, 0xffff0000, v101
	v_lshlrev_b32_e32 v104, 16, v105
	v_and_b32_e32 v105, 0xffff0000, v105
	v_pk_mul_f32 v[100:101], v[100:101], v[104:105]
	v_lshlrev_b32_e32 v104, 16, v106
	v_pk_mul_f32 v[78:79], v[78:79], v[100:101]
	v_lshlrev_b32_e32 v100, 16, v102
	v_and_b32_e32 v101, 0xffff0000, v102
	v_and_b32_e32 v105, 0xffff0000, v106
	v_pk_mul_f32 v[100:101], v[100:101], v[104:105]
	v_pk_mul_f32 v[68:69], v[68:69], s[36:37] op_sel_hi:[1,0]
	v_pk_mul_f32 v[100:101], v[72:73], v[100:101]
	v_pk_add_f32 v[72:73], v[74:75], 1.0 op_sel_hi:[1,0]
	v_exp_f32_e32 v68, v68
	v_rcp_f32_e32 v72, v72
	v_rcp_f32_e32 v73, v73
	v_exp_f32_e32 v69, v69
	v_pk_add_f32 v[70:71], v[70:71], v[46:47]
	v_pk_mul_f32 v[116:117], v[116:117], v[118:119]
	v_lshlrev_b32_e32 v74, 16, v103
	v_and_b32_e32 v75, 0xffff0000, v103
	v_lshlrev_b32_e32 v102, 16, v107
	v_and_b32_e32 v103, 0xffff0000, v107
	v_pk_mul_f32 v[70:71], v[70:71], s[36:37] op_sel_hi:[1,0]
	v_lshlrev_b64 v[114:115], 13, v[120:121]
	v_pk_mul_f32 v[76:77], v[76:77], v[116:117]
	v_pk_mul_f32 v[74:75], v[74:75], v[102:103]
	v_exp_f32_e32 v70, v70
	v_exp_f32_e32 v71, v71
	v_pk_add_f32 v[64:65], v[64:65], v[40:41]
	v_pk_mul_f32 v[102:103], v[72:73], v[74:75]
	v_cvt_pk_bf16_f32 v72, v76, v77
	v_lshl_add_u64 v[76:77], s[56:57], 0, v[114:115]
	v_pk_mul_f32 v[64:65], v[64:65], s[36:37] op_sel_hi:[1,0]
	v_lshl_add_u64 v[76:77], v[76:77], 0, v[198:199]
	v_pk_add_f32 v[68:69], v[68:69], 1.0 op_sel_hi:[1,0]
	v_exp_f32_e32 v64, v64
	v_exp_f32_e32 v65, v65
	v_add_co_u32_e32 v76, vcc, s81, v76
	v_rcp_f32_e32 v68, v68
	v_rcp_f32_e32 v69, v69
	v_cvt_pk_bf16_f32 v73, v78, v79
	v_cvt_pk_bf16_f32 v74, v100, v101
	v_cvt_pk_bf16_f32 v75, v102, v103
	v_addc_co_u32_e32 v77, vcc, 0, v77, vcc
	v_pk_add_f32 v[70:71], v[70:71], 1.0 op_sel_hi:[1,0]
	global_store_dwordx4 v[76:77], v[72:75], off sc1
	v_rcp_f32_e32 v70, v70
	v_rcp_f32_e32 v71, v71
	v_lshlrev_b32_e32 v72, 16, v108
	v_and_b32_e32 v73, 0xffff0000, v108
	v_lshlrev_b32_e32 v74, 16, v96
	v_and_b32_e32 v75, 0xffff0000, v96
	v_pk_add_f32 v[66:67], v[66:67], v[42:43]
	v_pk_mul_f32 v[72:73], v[72:73], v[74:75]
	v_pk_add_f32 v[64:65], v[64:65], 1.0 op_sel_hi:[1,0]
	v_pk_mul_f32 v[66:67], v[66:67], s[36:37] op_sel_hi:[1,0]
	v_pk_mul_f32 v[68:69], v[68:69], v[72:73]
	v_lshlrev_b32_e32 v72, 16, v109
	v_and_b32_e32 v73, 0xffff0000, v109
	v_lshlrev_b32_e32 v74, 16, v97
	v_and_b32_e32 v75, 0xffff0000, v97
	v_rcp_f32_e32 v64, v64
	v_rcp_f32_e32 v65, v65
	v_exp_f32_e32 v66, v66
	v_exp_f32_e32 v67, v67
	v_pk_add_f32 v[56:57], v[56:57], v[60:61]
	v_pk_mul_f32 v[72:73], v[72:73], v[74:75]
	v_pk_mul_f32 v[56:57], v[56:57], s[36:37] op_sel_hi:[1,0]
	v_pk_mul_f32 v[70:71], v[70:71], v[72:73]
	v_lshlrev_b32_e32 v72, 16, v110
	v_and_b32_e32 v73, 0xffff0000, v110
	v_lshlrev_b32_e32 v74, 16, v98
	v_and_b32_e32 v75, 0xffff0000, v98
	v_exp_f32_e32 v56, v56
	v_exp_f32_e32 v57, v57
	v_pk_add_f32 v[58:59], v[58:59], v[62:63]
	v_pk_mul_f32 v[72:73], v[72:73], v[74:75]
	v_pk_mul_f32 v[58:59], v[58:59], s[36:37] op_sel_hi:[1,0]
	v_pk_mul_f32 v[72:73], v[64:65], v[72:73]
	v_pk_add_f32 v[64:65], v[66:67], 1.0 op_sel_hi:[1,0]
	v_exp_f32_e32 v58, v58
	v_exp_f32_e32 v59, v59
	v_pk_add_f32 v[48:49], v[48:49], v[52:53]
	v_rcp_f32_e32 v64, v64
	v_rcp_f32_e32 v65, v65
	v_pk_mul_f32 v[48:49], v[48:49], s[36:37] op_sel_hi:[1,0]
	v_pk_add_f32 v[56:57], v[56:57], 1.0 op_sel_hi:[1,0]
	v_exp_f32_e32 v48, v48
	v_exp_f32_e32 v49, v49
	v_lshlrev_b32_e32 v66, 16, v111
	v_and_b32_e32 v67, 0xffff0000, v111
	v_lshlrev_b32_e32 v74, 16, v99
	v_and_b32_e32 v75, 0xffff0000, v99
	v_rcp_f32_e32 v56, v56
	v_rcp_f32_e32 v57, v57
	v_pk_add_f32 v[50:51], v[50:51], v[54:55]
	v_pk_mul_f32 v[66:67], v[66:67], v[74:75]
	v_pk_add_f32 v[58:59], v[58:59], 1.0 op_sel_hi:[1,0]
	v_pk_mul_f32 v[50:51], v[50:51], s[36:37] op_sel_hi:[1,0]
	v_pk_mul_f32 v[78:79], v[64:65], v[66:67]
	v_cvt_pk_bf16_f32 v65, v70, v71
	v_cvt_pk_bf16_f32 v66, v72, v73
	v_lshlrev_b32_e32 v70, 16, v88
	v_and_b32_e32 v71, 0xffff0000, v88
	v_lshlrev_b32_e32 v72, 16, v92
	v_and_b32_e32 v73, 0xffff0000, v92
	v_rcp_f32_e32 v58, v58
	v_rcp_f32_e32 v59, v59
	v_exp_f32_e32 v50, v50
	v_exp_f32_e32 v51, v51
	v_pk_mul_f32 v[70:71], v[70:71], v[72:73]
	v_pk_add_f32 v[48:49], v[48:49], 1.0 op_sel_hi:[1,0]
	v_pk_mul_f32 v[56:57], v[56:57], v[70:71]
	v_lshlrev_b32_e32 v70, 16, v89
	v_and_b32_e32 v71, 0xffff0000, v89
	v_lshlrev_b32_e32 v72, 16, v93
	v_and_b32_e32 v73, 0xffff0000, v93
	v_rcp_f32_e32 v48, v48
	v_rcp_f32_e32 v49, v49
	v_pk_mul_f32 v[70:71], v[70:71], v[72:73]
	v_lshlrev_b32_e32 v72, 16, v94
	v_pk_mul_f32 v[58:59], v[58:59], v[70:71]
	v_lshlrev_b32_e32 v70, 16, v90
	v_and_b32_e32 v71, 0xffff0000, v90
	v_and_b32_e32 v73, 0xffff0000, v94
	v_pk_add_f32 v[50:51], v[50:51], 1.0 op_sel_hi:[1,0]
	v_pk_add_f32 v[36:37], v[36:37], v[44:45]
	v_pk_mul_f32 v[70:71], v[70:71], v[72:73]
	v_rcp_f32_e32 v50, v50
	v_rcp_f32_e32 v51, v51
	v_pk_mul_f32 v[36:37], v[36:37], s[36:37] op_sel_hi:[1,0]
	v_cvt_pk_bf16_f32 v64, v68, v69
	v_lshlrev_b64 v[68:69], 13, v[112:113]
	v_pk_mul_f32 v[48:49], v[48:49], v[70:71]
	v_exp_f32_e32 v36, v36
	v_exp_f32_e32 v37, v37
	v_pk_add_f32 v[38:39], v[38:39], v[46:47]
	v_lshlrev_b32_e32 v70, 16, v91
	v_and_b32_e32 v71, 0xffff0000, v91
	v_lshlrev_b32_e32 v72, 16, v95
	v_and_b32_e32 v73, 0xffff0000, v95
	v_cvt_pk_bf16_f32 v56, v56, v57
	v_cvt_pk_bf16_f32 v57, v58, v59
	v_cvt_pk_bf16_f32 v58, v48, v49
	v_lshl_add_u64 v[48:49], s[56:57], 0, v[68:69]
	v_pk_mul_f32 v[38:39], v[38:39], s[36:37] op_sel_hi:[1,0]
	v_pk_mul_f32 v[70:71], v[70:71], v[72:73]
	v_lshl_add_u64 v[48:49], v[48:49], 0, v[198:199]
	v_add_u32_e32 v88, 0xa0, v200
	v_exp_f32_e32 v38, v38
	v_exp_f32_e32 v39, v39
	v_pk_add_f32 v[32:33], v[32:33], v[40:41]
	v_pk_mul_f32 v[50:51], v[50:51], v[70:71]
	v_add_co_u32_e32 v48, vcc, s81, v48
	v_ashrrev_i32_e32 v89, 31, v88
	v_pk_mul_f32 v[32:33], v[32:33], s[36:37] op_sel_hi:[1,0]
	v_cvt_pk_bf16_f32 v59, v50, v51
	v_addc_co_u32_e32 v49, vcc, 0, v49, vcc
	v_lshlrev_b64 v[50:51], 12, v[88:89]
	v_pk_add_f32 v[36:37], v[36:37], 1.0 op_sel_hi:[1,0]
	v_exp_f32_e32 v32, v32
	v_exp_f32_e32 v33, v33
	global_store_dwordx4 v[48:49], v[56:59], off sc1
	v_rcp_f32_e32 v36, v36
	v_rcp_f32_e32 v37, v37
	v_lshl_add_u64 v[56:57], v[202:203], 0, v[50:51]
	v_lshl_add_u64 v[50:51], v[204:205], 0, v[50:51]
	global_load_dwordx4 v[68:71], v[56:57], off
	global_load_dwordx4 v[72:75], v[50:51], off
	v_pk_add_f32 v[38:39], v[38:39], 1.0 op_sel_hi:[1,0]
	v_cvt_pk_bf16_f32 v67, v78, v79
	global_store_dwordx4 v[76:77], v[64:67], off offset:256 sc1
	v_lshlrev_b32_e32 v58, 16, v80
	v_and_b32_e32 v59, 0xffff0000, v80
	v_lshlrev_b32_e32 v64, 16, v84
	v_and_b32_e32 v65, 0xffff0000, v84
	v_rcp_f32_e32 v38, v38
	v_rcp_f32_e32 v39, v39
	v_pk_add_f32 v[34:35], v[34:35], v[42:43]
	v_pk_mul_f32 v[58:59], v[58:59], v[64:65]
	v_pk_add_f32 v[32:33], v[32:33], 1.0 op_sel_hi:[1,0]
	v_pk_mul_f32 v[34:35], v[34:35], s[36:37] op_sel_hi:[1,0]
	v_pk_mul_f32 v[36:37], v[36:37], v[58:59]
	v_lshlrev_b32_e32 v58, 16, v81
	v_and_b32_e32 v59, 0xffff0000, v81
	v_lshlrev_b32_e32 v64, 16, v85
	v_and_b32_e32 v65, 0xffff0000, v85
	v_rcp_f32_e32 v32, v32
	v_rcp_f32_e32 v33, v33
	v_exp_f32_e32 v34, v34
	v_exp_f32_e32 v35, v35
	v_pk_mul_f32 v[58:59], v[58:59], v[64:65]
	v_lshlrev_b32_e32 v64, 16, v86
	v_pk_mul_f32 v[38:39], v[38:39], v[58:59]
	v_lshlrev_b32_e32 v58, 16, v82
	v_and_b32_e32 v59, 0xffff0000, v82
	v_and_b32_e32 v65, 0xffff0000, v86
	v_pk_mul_f32 v[58:59], v[58:59], v[64:65]
	v_lshlrev_b32_e32 v64, 16, v87
	v_pk_mul_f32 v[58:59], v[32:33], v[58:59]
	v_pk_add_f32 v[32:33], v[34:35], 1.0 op_sel_hi:[1,0]
	v_lshlrev_b32_e32 v34, 16, v83
	v_rcp_f32_e32 v32, v32
	v_rcp_f32_e32 v33, v33
	v_and_b32_e32 v35, 0xffff0000, v83
	v_and_b32_e32 v65, 0xffff0000, v87
	v_pk_mul_f32 v[34:35], v[34:35], v[64:65]
	v_add_u32_e32 v80, 0xb0, v200
	v_pk_mul_f32 v[64:65], v[32:33], v[34:35]
	v_cvt_pk_bf16_f32 v32, v36, v37
	v_cvt_pk_bf16_f32 v33, v38, v39
	v_cvt_pk_bf16_f32 v34, v58, v59
	v_ashrrev_i32_e32 v81, 31, v80
	v_cvt_pk_bf16_f32 v35, v64, v65
	global_store_dwordx4 v[48:49], v[32:35], off offset:256 sc1
	global_load_dwordx4 v[76:79], v[56:57], off offset:256
	global_load_dwordx4 v[64:67], v[50:51], off offset:256
	v_lshlrev_b64 v[32:33], 12, v[80:81]
	v_lshl_add_u64 v[34:35], v[202:203], 0, v[32:33]
	v_lshl_add_u64 v[36:37], v[204:205], 0, v[32:33]
	global_load_dwordx4 v[48:51], v[34:35], off
	s_nop 0
	global_load_dwordx4 v[32:35], v[34:35], off offset:256
	s_nop 0
	global_load_dwordx4 v[56:59], v[36:37], off
	s_nop 0
	global_load_dwordx4 v[36:39], v[36:37], off offset:256
	v_pk_add_f32 v[30:31], v[30:31], v[62:63]
	v_pk_add_f32 v[24:25], v[24:25], v[52:53]
	v_pk_mul_f32 v[30:31], v[30:31], s[36:37] op_sel_hi:[1,0]
	v_pk_mul_f32 v[24:25], v[24:25], s[36:37] op_sel_hi:[1,0]
	v_exp_f32_e32 v30, v30
	v_exp_f32_e32 v31, v31
	v_exp_f32_e32 v24, v24
	v_exp_f32_e32 v25, v25
	v_pk_add_f32 v[28:29], v[28:29], v[60:61]
	v_pk_add_f32 v[30:31], v[30:31], 1.0 op_sel_hi:[1,0]
	v_pk_mul_f32 v[28:29], v[28:29], s[36:37] op_sel_hi:[1,0]
	v_rcp_f32_e32 v30, v30
	v_rcp_f32_e32 v31, v31
	v_pk_add_f32 v[26:27], v[26:27], v[54:55]
	v_exp_f32_e32 v28, v28
	v_exp_f32_e32 v29, v29
	v_pk_add_f32 v[24:25], v[24:25], 1.0 op_sel_hi:[1,0]
	v_pk_mul_f32 v[26:27], v[26:27], s[36:37] op_sel_hi:[1,0]
	v_rcp_f32_e32 v24, v24
	v_rcp_f32_e32 v25, v25
	v_exp_f32_e32 v26, v26
	v_exp_f32_e32 v27, v27
	v_pk_add_f32 v[28:29], v[28:29], 1.0 op_sel_hi:[1,0]
	v_pk_add_f32 v[20:21], v[20:21], v[44:45]
	v_rcp_f32_e32 v28, v28
	v_rcp_f32_e32 v29, v29
	s_waitcnt vmcnt(0)
	v_lshlrev_b32_e32 v84, 16, v68
	v_and_b32_e32 v85, 0xffff0000, v68
	v_lshlrev_b32_e32 v86, 16, v72
	v_and_b32_e32 v87, 0xffff0000, v72
	v_lshlrev_b32_e32 v68, 16, v69
	v_and_b32_e32 v69, 0xffff0000, v69
	v_lshlrev_b32_e32 v72, 16, v73
	v_and_b32_e32 v73, 0xffff0000, v73
	v_pk_mul_f32 v[68:69], v[68:69], v[72:73]
	v_lshlrev_b32_e32 v72, 16, v74
	v_pk_mul_f32 v[30:31], v[30:31], v[68:69]
	v_lshlrev_b32_e32 v68, 16, v70
	v_and_b32_e32 v69, 0xffff0000, v70
	v_and_b32_e32 v73, 0xffff0000, v74
	v_pk_mul_f32 v[68:69], v[68:69], v[72:73]
	v_pk_mul_f32 v[20:21], v[20:21], s[36:37] op_sel_hi:[1,0]
	v_pk_mul_f32 v[68:69], v[24:25], v[68:69]
	v_pk_add_f32 v[24:25], v[26:27], 1.0 op_sel_hi:[1,0]
	v_exp_f32_e32 v20, v20
	v_rcp_f32_e32 v24, v24
	v_rcp_f32_e32 v25, v25
	v_exp_f32_e32 v21, v21
	v_pk_add_f32 v[22:23], v[22:23], v[46:47]
	v_pk_mul_f32 v[84:85], v[84:85], v[86:87]
	v_lshlrev_b32_e32 v26, 16, v71
	v_and_b32_e32 v27, 0xffff0000, v71
	v_lshlrev_b32_e32 v70, 16, v75
	v_and_b32_e32 v71, 0xffff0000, v75
	v_pk_mul_f32 v[22:23], v[22:23], s[36:37] op_sel_hi:[1,0]
	v_lshlrev_b64 v[82:83], 13, v[88:89]
	v_pk_mul_f32 v[28:29], v[28:29], v[84:85]
	v_pk_mul_f32 v[26:27], v[26:27], v[70:71]
	v_exp_f32_e32 v22, v22
	v_exp_f32_e32 v23, v23
	v_pk_add_f32 v[16:17], v[16:17], v[40:41]
	v_pk_mul_f32 v[70:71], v[24:25], v[26:27]
	v_cvt_pk_bf16_f32 v24, v28, v29
	v_lshl_add_u64 v[28:29], s[56:57], 0, v[82:83]
	v_pk_mul_f32 v[16:17], v[16:17], s[36:37] op_sel_hi:[1,0]
	v_lshl_add_u64 v[28:29], v[28:29], 0, v[198:199]
	v_pk_add_f32 v[20:21], v[20:21], 1.0 op_sel_hi:[1,0]
	v_exp_f32_e32 v16, v16
	v_exp_f32_e32 v17, v17
	v_add_co_u32_e32 v28, vcc, s81, v28
	v_rcp_f32_e32 v20, v20
	v_rcp_f32_e32 v21, v21
	v_cvt_pk_bf16_f32 v25, v30, v31
	v_cvt_pk_bf16_f32 v26, v68, v69
	v_cvt_pk_bf16_f32 v27, v70, v71
	v_addc_co_u32_e32 v29, vcc, 0, v29, vcc
	v_pk_add_f32 v[22:23], v[22:23], 1.0 op_sel_hi:[1,0]
	global_store_dwordx4 v[28:29], v[24:27], off sc1
	v_rcp_f32_e32 v22, v22
	v_rcp_f32_e32 v23, v23
	v_lshlrev_b32_e32 v24, 16, v76
	v_and_b32_e32 v25, 0xffff0000, v76
	v_lshlrev_b32_e32 v26, 16, v64
	v_and_b32_e32 v27, 0xffff0000, v64
	v_pk_add_f32 v[18:19], v[18:19], v[42:43]
	v_pk_mul_f32 v[24:25], v[24:25], v[26:27]
	v_pk_add_f32 v[16:17], v[16:17], 1.0 op_sel_hi:[1,0]
	v_pk_mul_f32 v[18:19], v[18:19], s[36:37] op_sel_hi:[1,0]
	v_pk_mul_f32 v[20:21], v[20:21], v[24:25]
	v_lshlrev_b32_e32 v24, 16, v77
	v_and_b32_e32 v25, 0xffff0000, v77
	v_lshlrev_b32_e32 v26, 16, v65
	v_and_b32_e32 v27, 0xffff0000, v65
	v_rcp_f32_e32 v16, v16
	v_rcp_f32_e32 v17, v17
	v_exp_f32_e32 v18, v18
	v_exp_f32_e32 v19, v19
	v_pk_mul_f32 v[24:25], v[24:25], v[26:27]
	v_pk_add_f32 v[12:13], v[12:13], v[60:61]
	v_pk_mul_f32 v[22:23], v[22:23], v[24:25]
	v_lshlrev_b32_e32 v24, 16, v78
	v_and_b32_e32 v25, 0xffff0000, v78
	v_lshlrev_b32_e32 v26, 16, v66
	v_and_b32_e32 v27, 0xffff0000, v66
	v_pk_mul_f32 v[12:13], v[12:13], s[36:37] op_sel_hi:[1,0]
	v_pk_mul_f32 v[24:25], v[24:25], v[26:27]
	v_exp_f32_e32 v12, v12
	v_exp_f32_e32 v13, v13
	v_pk_add_f32 v[14:15], v[14:15], v[62:63]
	v_pk_mul_f32 v[24:25], v[16:17], v[24:25]
	v_pk_add_f32 v[16:17], v[18:19], 1.0 op_sel_hi:[1,0]
	v_pk_mul_f32 v[14:15], v[14:15], s[36:37] op_sel_hi:[1,0]
	v_rcp_f32_e32 v16, v16
	v_rcp_f32_e32 v17, v17
	v_exp_f32_e32 v14, v14
	v_exp_f32_e32 v15, v15
	v_pk_add_f32 v[8:9], v[8:9], v[52:53]
	v_lshlrev_b32_e32 v18, 16, v79
	v_pk_mul_f32 v[8:9], v[8:9], s[36:37] op_sel_hi:[1,0]
	v_and_b32_e32 v19, 0xffff0000, v79
	v_lshlrev_b32_e32 v26, 16, v67
	v_and_b32_e32 v27, 0xffff0000, v67
	v_pk_add_f32 v[12:13], v[12:13], 1.0 op_sel_hi:[1,0]
	v_exp_f32_e32 v8, v8
	v_exp_f32_e32 v9, v9
	v_pk_mul_f32 v[18:19], v[18:19], v[26:27]
	v_rcp_f32_e32 v12, v12
	v_rcp_f32_e32 v13, v13
	v_pk_mul_f32 v[26:27], v[16:17], v[18:19]
	v_cvt_pk_bf16_f32 v18, v24, v25
	v_pk_add_f32 v[14:15], v[14:15], 1.0 op_sel_hi:[1,0]
	v_cvt_pk_bf16_f32 v19, v26, v27
	v_cvt_pk_bf16_f32 v16, v20, v21
	v_cvt_pk_bf16_f32 v17, v22, v23
	global_store_dwordx4 v[28:29], v[16:19], off offset:256 sc1
	v_lshlrev_b32_e32 v20, 16, v56
	v_and_b32_e32 v21, 0xffff0000, v56
	v_lshlrev_b32_e32 v18, 16, v48
	v_and_b32_e32 v19, 0xffff0000, v48
	v_rcp_f32_e32 v14, v14
	v_rcp_f32_e32 v15, v15
	v_pk_add_f32 v[10:11], v[10:11], v[54:55]
	v_pk_mul_f32 v[18:19], v[18:19], v[20:21]
	v_pk_add_f32 v[8:9], v[8:9], 1.0 op_sel_hi:[1,0]
	v_pk_mul_f32 v[10:11], v[10:11], s[36:37] op_sel_hi:[1,0]
	v_pk_mul_f32 v[12:13], v[12:13], v[18:19]
	v_lshlrev_b32_e32 v18, 16, v49
	v_and_b32_e32 v19, 0xffff0000, v49
	v_lshlrev_b32_e32 v20, 16, v57
	v_and_b32_e32 v21, 0xffff0000, v57
	v_rcp_f32_e32 v8, v8
	v_rcp_f32_e32 v9, v9
	v_exp_f32_e32 v10, v10
	v_exp_f32_e32 v11, v11
	v_pk_mul_f32 v[18:19], v[18:19], v[20:21]
	v_lshlrev_b32_e32 v20, 16, v58
	v_pk_mul_f32 v[14:15], v[14:15], v[18:19]
	v_lshlrev_b32_e32 v18, 16, v50
	v_and_b32_e32 v19, 0xffff0000, v50
	v_and_b32_e32 v21, 0xffff0000, v58
	v_pk_mul_f32 v[18:19], v[18:19], v[20:21]
	v_pk_add_f32 v[4:5], v[4:5], v[44:45]
	v_pk_mul_f32 v[18:19], v[8:9], v[18:19]
	v_pk_add_f32 v[8:9], v[10:11], 1.0 op_sel_hi:[1,0]
	v_pk_mul_f32 v[4:5], v[4:5], s[36:37] op_sel_hi:[1,0]
	v_rcp_f32_e32 v8, v8
	v_rcp_f32_e32 v9, v9
	v_exp_f32_e32 v4, v4
	v_exp_f32_e32 v5, v5
	v_pk_add_f32 v[6:7], v[6:7], v[46:47]
	v_lshlrev_b32_e32 v10, 16, v51
	v_and_b32_e32 v11, 0xffff0000, v51
	v_lshlrev_b32_e32 v20, 16, v59
	v_and_b32_e32 v21, 0xffff0000, v59
	v_pk_mul_f32 v[6:7], v[6:7], s[36:37] op_sel_hi:[1,0]
	v_lshlrev_b64 v[16:17], 13, v[80:81]
	v_pk_mul_f32 v[10:11], v[10:11], v[20:21]
	v_exp_f32_e32 v6, v6
	v_exp_f32_e32 v7, v7
	v_pk_add_f32 v[0:1], v[0:1], v[40:41]
	v_pk_mul_f32 v[20:21], v[8:9], v[10:11]
	v_cvt_pk_bf16_f32 v8, v12, v13
	v_lshl_add_u64 v[12:13], s[56:57], 0, v[16:17]
	v_pk_mul_f32 v[0:1], v[0:1], s[36:37] op_sel_hi:[1,0]
	v_lshl_add_u64 v[12:13], v[12:13], 0, v[198:199]
	v_pk_add_f32 v[4:5], v[4:5], 1.0 op_sel_hi:[1,0]
	v_exp_f32_e32 v0, v0
	v_exp_f32_e32 v1, v1
	v_add_co_u32_e32 v12, vcc, s81, v12
	v_rcp_f32_e32 v4, v4
	v_rcp_f32_e32 v5, v5
	v_cvt_pk_bf16_f32 v9, v14, v15
	v_cvt_pk_bf16_f32 v10, v18, v19
	v_cvt_pk_bf16_f32 v11, v20, v21
	v_addc_co_u32_e32 v13, vcc, 0, v13, vcc
	v_pk_add_f32 v[6:7], v[6:7], 1.0 op_sel_hi:[1,0]
	global_store_dwordx4 v[12:13], v[8:11], off sc1
	v_rcp_f32_e32 v6, v6
	v_rcp_f32_e32 v7, v7
	v_lshlrev_b32_e32 v8, 16, v32
	v_and_b32_e32 v9, 0xffff0000, v32
	v_lshlrev_b32_e32 v10, 16, v36
	v_and_b32_e32 v11, 0xffff0000, v36
	v_pk_add_f32 v[2:3], v[2:3], v[42:43]
	v_pk_mul_f32 v[8:9], v[8:9], v[10:11]
	v_pk_add_f32 v[0:1], v[0:1], 1.0 op_sel_hi:[1,0]
	v_pk_mul_f32 v[2:3], v[2:3], s[36:37] op_sel_hi:[1,0]
	v_pk_mul_f32 v[4:5], v[4:5], v[8:9]
	v_lshlrev_b32_e32 v8, 16, v33
	v_and_b32_e32 v9, 0xffff0000, v33
	v_lshlrev_b32_e32 v10, 16, v37
	v_and_b32_e32 v11, 0xffff0000, v37
	v_rcp_f32_e32 v0, v0
	v_rcp_f32_e32 v1, v1
	v_exp_f32_e32 v2, v2
	v_exp_f32_e32 v3, v3
	v_pk_mul_f32 v[8:9], v[8:9], v[10:11]
	v_lshlrev_b32_e32 v10, 16, v38
	v_pk_mul_f32 v[6:7], v[6:7], v[8:9]
	v_lshlrev_b32_e32 v8, 16, v34
	v_and_b32_e32 v9, 0xffff0000, v34
	v_and_b32_e32 v11, 0xffff0000, v38
	v_pk_mul_f32 v[8:9], v[8:9], v[10:11]
	v_lshlrev_b32_e32 v10, 16, v39
	v_pk_mul_f32 v[8:9], v[0:1], v[8:9]
	v_pk_add_f32 v[0:1], v[2:3], 1.0 op_sel_hi:[1,0]
	v_lshlrev_b32_e32 v2, 16, v35
	v_rcp_f32_e32 v0, v0
	v_rcp_f32_e32 v1, v1
	v_and_b32_e32 v3, 0xffff0000, v35
	v_and_b32_e32 v11, 0xffff0000, v39
	v_pk_mul_f32 v[2:3], v[2:3], v[10:11]
	s_nop 0
	v_pk_mul_f32 v[10:11], v[0:1], v[2:3]
	v_cvt_pk_bf16_f32 v0, v4, v5
	v_cvt_pk_bf16_f32 v1, v6, v7
	v_cvt_pk_bf16_f32 v2, v8, v9
	s_nop 0
	v_cvt_pk_bf16_f32 v3, v10, v11
	global_store_dwordx4 v[12:13], v[0:3], off offset:256 sc1
	s_or_b64 s[10:11], s[24:25], s[50:51]
	s_and_b64 vcc, exec, s[10:11]
	s_cbranch_vccnz .LBB0_544

.LBB0_581:
	s_or_b64 exec, exec, s[10:11]
	s_and_b64 s[10:11], exec, s[16:17]
	s_cselect_b32 s5, 8, 1
	v_cvt_f32_ubyte0_e32 v0, s5
	v_rcp_iflag_f32_e32 v0, v0
	s_sub_i32 s10, s4, s33
	s_addk_i32 s10, 0x120
	s_ashr_i32 s11, s10, 31
	s_lshr_b32 s11, s11, 29
	v_mul_f32_e32 v0, 0x4f7ffffe, v0
	s_add_i32 s11, s10, s11
	v_cvt_u32_f32_e32 v0, v0
	s_ashr_i32 s16, s11, 3
	s_and_b32 s11, s11, -8
	s_sub_i32 s10, s10, s11
	s_cmp_lt_i32 s10, 0
	s_cselect_b32 s11, 37, 36
	s_sub_i32 s17, 0, s5
	v_readfirstlane_b32 s18, v0
	s_mul_i32 s17, s17, s18
	s_mul_hi_u32 s17, s18, s17
	s_mul_i32 s10, s10, s11
	s_abs_i32 s11, s2
	s_add_i32 s18, s18, s17
	s_mul_hi_u32 s17, s11, s18
	s_mul_i32 s17, s17, s5
	s_sub_i32 s11, s11, s17
	s_sub_i32 s17, s11, s5
	s_cmp_ge_u32 s11, s5
	s_cselect_b32 s11, s17, s11
	s_sub_i32 s17, s11, s5
	s_cmp_ge_u32 s11, s5
	s_cselect_b32 s5, s17, s11
	s_add_i32 s10, s10, s16
	s_ashr_i32 s11, s10, 31
	s_lshr_b32 s11, s11, 26
	s_add_i32 s11, s10, s11
	s_ashr_i32 s16, s11, 6
	s_lshl_b32 s16, s16, 3
	s_sub_i32 s17, 36, s16
	s_min_i32 s17, s17, 8
	s_abs_i32 s18, s17
	v_cvt_f32_u32_e32 v0, s18
	s_sub_i32 s19, 0, s18
	s_xor_b32 s5, s5, s3
	s_andn2_b32 s11, s11, 63
	v_rcp_iflag_f32_e32 v0, v0
	s_sub_i32 s3, s5, s3
	s_sub_i32 s5, s10, s11
	s_abs_i32 s11, s5
	v_mul_f32_e32 v0, 0x4f7ffffe, v0
	v_cvt_u32_f32_e32 v0, v0
	s_xor_b32 s10, s5, s17
	s_ashr_i32 s10, s10, 31
	v_lshl_add_u32 v44, s3, 5, v179
	v_readfirstlane_b32 s20, v0
	s_mul_i32 s19, s19, s20
	s_mul_hi_u32 s19, s20, s19
	s_add_i32 s20, s20, s19
	s_mul_hi_u32 s19, s11, s20
	s_mul_i32 s20, s19, s18
	s_sub_i32 s11, s11, s20
	s_add_i32 s20, s19, 1
	s_sub_i32 s21, s11, s18
	s_cmp_ge_u32 s11, s18
	s_cselect_b32 s19, s20, s19
	s_cselect_b32 s11, s21, s11
	s_add_i32 s20, s19, 1
	s_cmp_ge_u32 s11, s18
	s_cselect_b32 s11, s20, s19
	s_xor_b32 s11, s11, s10
	s_sub_i32 s10, s11, s10
	s_mul_i32 s11, s10, s17
	v_ashrrev_i32_e32 v0, 7, v44
	v_lshrrev_b32_e32 v2, 3, v44
	v_and_b32_e32 v4, 6, v180
	s_sub_i32 s5, s5, s11
	v_and_b32_e32 v3, 8, v2
	v_add_u32_e32 v0, v0, v4
	s_add_i32 s16, s16, s5
	s_ashr_i32 s5, s4, 31
	v_bfe_u32 v1, v223, 7, 1
	v_add_lshl_u32 v0, v0, v3, 3
	v_and_b32_e32 v2, 6, v2
	s_lshl_b64 s[4:5], s[4:5], 17
	v_or3_b32 v0, v0, v2, v1
	s_add_u32 s4, s58, s4
	v_ashrrev_i32_e32 v1, 31, v0
	s_addc_u32 s5, s59, s5
	v_and_or_b32 v2, v179, 15, v213
	v_lshlrev_b64 v[0:1], 10, v[0:1]
	v_lshl_add_u64 v[0:1], s[4:5], 0, v[0:1]
	v_lshlrev_b32_e32 v2, 4, v2
	v_mov_b32_e32 v3, 0
	v_lshl_add_u64 v[2:3], v[0:1], 0, v[2:3]
	v_and_b32_e32 v0, 0xf0, v223
	v_lshl_or_b32 v0, s10, 8, v0
	v_readlane_b32 s20, v254, 0
	v_ashrrev_i32_e32 v1, 31, v0
	v_readlane_b32 s24, v254, 4
	v_readlane_b32 s25, v254, 5
	s_mov_b32 s3, 0x400000
	s_waitcnt vmcnt(0) lgkmcnt(0)
	v_lshl_add_u64 v[8:9], v[0:1], 2, s[24:25]
	s_barrier
	global_load_dwordx4 v[4:7], v[2:3], off
	global_load_dwordx4 v[10:13], v[2:3], off offset:256
	global_load_dwordx4 v[14:17], v[8:9], off offset:16
	global_load_dwordx4 v[18:21], v[8:9], off
	global_load_dwordx4 v[22:25], v[8:9], off offset:48
	global_load_dwordx4 v[26:29], v[8:9], off offset:32
	v_add_co_u32_e32 v8, vcc, s3, v2
	s_mov_b32 s3, 0x800000
	s_nop 0
	v_addc_co_u32_e32 v9, vcc, 0, v3, vcc
	global_load_dwordx4 v[30:33], v[8:9], off
	global_load_dwordx4 v[34:37], v[8:9], off offset:256
	v_add_co_u32_e32 v42, vcc, s3, v2
	s_mov_b32 s3, 0xc00000
	s_nop 0
	v_addc_co_u32_e32 v43, vcc, 0, v3, vcc
	v_add_co_u32_e32 v50, vcc, s3, v2
	global_load_dwordx4 v[38:41], v[42:43], off
	s_nop 0
	v_addc_co_u32_e32 v51, vcc, 0, v3, vcc
	v_lshl_add_u32 v8, s16, 8, v44
	global_load_dwordx4 v[46:49], v[50:51], off
	s_mov_b32 s3, 0x1000000
	global_load_dwordx4 v[42:45], v[42:43], off offset:256
	v_ashrrev_i32_e32 v9, 31, v8
	s_mov_b64 s[4:5], 0x1000
	v_readlane_b32 s21, v254, 1
	v_readlane_b32 s22, v254, 2
	v_readlane_b32 s23, v254, 3
	v_readlane_b32 s26, v254, 6
	v_readlane_b32 s27, v254, 7
	s_waitcnt vmcnt(10)
	v_lshlrev_b32_e32 v52, 16, v4
	v_and_b32_e32 v53, 0xffff0000, v4
	v_lshlrev_b32_e32 v4, 16, v5
	v_and_b32_e32 v5, 0xffff0000, v5
	v_lshlrev_b32_e32 v54, 16, v6
	v_and_b32_e32 v55, 0xffff0000, v6
	v_lshlrev_b32_e32 v6, 16, v7
	v_and_b32_e32 v7, 0xffff0000, v7
	s_waitcnt vmcnt(9)
	v_lshlrev_b32_e32 v56, 16, v10
	v_and_b32_e32 v57, 0xffff0000, v10
	v_lshlrev_b32_e32 v10, 16, v11
	v_and_b32_e32 v11, 0xffff0000, v11
	v_lshlrev_b32_e32 v58, 16, v12
	v_and_b32_e32 v59, 0xffff0000, v12
	v_lshlrev_b32_e32 v12, 16, v13
	v_and_b32_e32 v13, 0xffff0000, v13
	s_waitcnt vmcnt(7)
	v_pk_add_f32 v[20:21], v[20:21], v[4:5]
	v_pk_add_f32 v[16:17], v[16:17], v[6:7]
	global_load_dwordx4 v[4:7], v[50:51], off offset:256
	v_add_co_u32_e32 v50, vcc, s3, v2
	v_pk_add_f32 v[18:19], v[18:19], v[52:53]
	s_waitcnt vmcnt(6)
	v_pk_add_f32 v[28:29], v[28:29], v[10:11]
	v_pk_add_f32 v[24:25], v[24:25], v[12:13]
	s_waitcnt vmcnt(5)
	v_lshlrev_b32_e32 v10, 16, v30
	v_and_b32_e32 v11, 0xffff0000, v30
	v_lshlrev_b32_e32 v12, 16, v31
	v_and_b32_e32 v13, 0xffff0000, v31
	v_addc_co_u32_e32 v51, vcc, 0, v3, vcc
	v_pk_add_f32 v[20:21], v[20:21], v[12:13]
	v_pk_add_f32 v[18:19], v[18:19], v[10:11]
	global_load_dwordx4 v[10:13], v[50:51], off
	v_pk_add_f32 v[14:15], v[14:15], v[54:55]
	v_lshlrev_b32_e32 v30, 16, v32
	v_and_b32_e32 v31, 0xffff0000, v32
	v_lshlrev_b32_e32 v32, 16, v33
	v_and_b32_e32 v33, 0xffff0000, v33
	v_pk_add_f32 v[26:27], v[26:27], v[56:57]
	v_pk_add_f32 v[32:33], v[16:17], v[32:33]
	v_pk_add_f32 v[30:31], v[14:15], v[30:31]
	s_waitcnt vmcnt(5)
	v_lshlrev_b32_e32 v14, 16, v34
	v_and_b32_e32 v15, 0xffff0000, v34
	v_lshlrev_b32_e32 v16, 16, v35
	v_and_b32_e32 v17, 0xffff0000, v35
	v_pk_add_f32 v[22:23], v[22:23], v[58:59]
	v_pk_add_f32 v[28:29], v[28:29], v[16:17]
	v_pk_add_f32 v[26:27], v[26:27], v[14:15]
	v_lshlrev_b32_e32 v14, 16, v36
	v_and_b32_e32 v15, 0xffff0000, v36
	v_lshlrev_b32_e32 v16, 16, v37
	v_and_b32_e32 v17, 0xffff0000, v37
	v_pk_add_f32 v[24:25], v[24:25], v[16:17]
	v_pk_add_f32 v[22:23], v[22:23], v[14:15]
	global_load_dwordx4 v[14:17], v[50:51], off offset:256
	s_waitcnt vmcnt(5)
	v_lshlrev_b32_e32 v34, 16, v38
	v_and_b32_e32 v35, 0xffff0000, v38
	v_lshlrev_b32_e32 v36, 16, v39
	v_and_b32_e32 v37, 0xffff0000, v39
	v_lshlrev_b32_e32 v38, 16, v40
	v_and_b32_e32 v39, 0xffff0000, v40
	s_mov_b32 s3, 0x1400000
	v_lshlrev_b32_e32 v40, 16, v41
	v_and_b32_e32 v41, 0xffff0000, v41
	v_add_co_u32_e32 v50, vcc, s3, v2
	v_pk_add_f32 v[30:31], v[30:31], v[38:39]
	v_pk_add_f32 v[32:33], v[32:33], v[40:41]
	s_waitcnt vmcnt(3)
	v_lshlrev_b32_e32 v38, 16, v42
	v_and_b32_e32 v39, 0xffff0000, v42
	v_lshlrev_b32_e32 v40, 16, v43
	v_and_b32_e32 v41, 0xffff0000, v43
	v_addc_co_u32_e32 v51, vcc, 0, v3, vcc
	v_pk_add_f32 v[38:39], v[26:27], v[38:39]
	v_pk_add_f32 v[40:41], v[28:29], v[40:41]
	v_lshlrev_b32_e32 v26, 16, v44
	v_and_b32_e32 v27, 0xffff0000, v44
	v_lshlrev_b32_e32 v28, 16, v45
	v_and_b32_e32 v29, 0xffff0000, v45
	v_pk_add_f32 v[34:35], v[18:19], v[34:35]
	v_pk_add_f32 v[36:37], v[20:21], v[36:37]
	global_load_dwordx4 v[18:21], v[50:51], off
	v_pk_add_f32 v[42:43], v[22:23], v[26:27]
	v_pk_add_f32 v[44:45], v[24:25], v[28:29]
	v_lshlrev_b32_e32 v22, 16, v46
	v_and_b32_e32 v23, 0xffff0000, v46
	v_lshlrev_b32_e32 v24, 16, v47
	v_and_b32_e32 v25, 0xffff0000, v47
	v_lshlrev_b32_e32 v26, 16, v48
	v_and_b32_e32 v27, 0xffff0000, v48
	s_mov_b32 s3, 0x1800000
	v_pk_add_f32 v[46:47], v[36:37], v[24:25]
	v_pk_add_f32 v[34:35], v[34:35], v[22:23]
	global_load_dwordx4 v[22:25], v[50:51], off offset:256
	v_pk_add_f32 v[50:51], v[30:31], v[26:27]
	v_add_co_u32_e32 v30, vcc, s3, v2
	v_lshlrev_b32_e32 v28, 16, v49
	v_and_b32_e32 v29, 0xffff0000, v49
	v_addc_co_u32_e32 v31, vcc, 0, v3, vcc
	v_pk_add_f32 v[48:49], v[32:33], v[28:29]
	global_load_dwordx4 v[26:29], v[30:31], off
	s_waitcnt vmcnt(5)
	v_lshlrev_b32_e32 v32, 16, v4
	v_and_b32_e32 v33, 0xffff0000, v4
	s_mov_b32 s3, 0x1c00000
	v_lshlrev_b32_e32 v4, 16, v5
	v_and_b32_e32 v5, 0xffff0000, v5
	v_pk_add_f32 v[38:39], v[38:39], v[32:33]
	v_lshlrev_b32_e32 v36, 16, v6
	v_and_b32_e32 v37, 0xffff0000, v6
	global_load_dwordx4 v[30:33], v[30:31], off offset:256
	v_add_co_u32_e32 v2, vcc, s3, v2
	v_pk_add_f32 v[4:5], v[40:41], v[4:5]
	v_pk_add_f32 v[40:41], v[42:43], v[36:37]
	s_waitcnt vmcnt(5)
	v_lshlrev_b32_e32 v36, 16, v10
	v_and_b32_e32 v37, 0xffff0000, v10
	v_addc_co_u32_e32 v3, vcc, 0, v3, vcc
	v_pk_add_f32 v[52:53], v[34:35], v[36:37]
	global_load_dwordx4 v[34:37], v[2:3], off
	v_lshlrev_b32_e32 v10, 16, v11
	v_and_b32_e32 v11, 0xffff0000, v11
	v_pk_add_f32 v[46:47], v[46:47], v[10:11]
	v_lshlrev_b32_e32 v10, 16, v12
	v_and_b32_e32 v11, 0xffff0000, v12
	v_lshlrev_b32_e32 v12, 16, v13
	v_and_b32_e32 v13, 0xffff0000, v13
	v_pk_add_f32 v[50:51], v[50:51], v[10:11]
	v_pk_add_f32 v[48:49], v[48:49], v[12:13]
	v_lshlrev_b32_e32 v6, 16, v7
	v_and_b32_e32 v7, 0xffff0000, v7
	s_waitcnt vmcnt(5)
	v_lshlrev_b32_e32 v10, 16, v14
	v_and_b32_e32 v11, 0xffff0000, v14
	v_lshlrev_b32_e32 v42, 16, v15
	v_and_b32_e32 v43, 0xffff0000, v15
	global_load_dwordx4 v[12:15], v[2:3], off offset:256
	v_pk_add_f32 v[6:7], v[44:45], v[6:7]
	v_pk_add_f32 v[56:57], v[4:5], v[42:43]
	v_lshlrev_b32_e32 v4, 16, v17
	v_and_b32_e32 v5, 0xffff0000, v17
	v_lshlrev_b32_e32 v2, 16, v16
	v_and_b32_e32 v3, 0xffff0000, v16
	v_pk_add_f32 v[58:59], v[6:7], v[4:5]
	v_lshlrev_b64 v[4:5], 12, v[8:9]
	v_pk_add_f32 v[54:55], v[38:39], v[10:11]
	v_pk_add_f32 v[16:17], v[40:41], v[2:3]
	v_lshl_add_u64 v[2:3], s[8:9], 0, v[4:5]
	v_lshlrev_b64 v[10:11], 1, v[0:1]
	v_lshl_add_u64 v[6:7], v[2:3], 0, v[10:11]
	v_lshl_add_u64 v[4:5], s[6:7], 0, v[4:5]
	global_load_dwordx4 v[0:3], v[6:7], off offset:16
	global_load_dwordx4 v[38:41], v[6:7], off
	v_lshl_add_u64 v[62:63], v[4:5], 0, v[10:11]
	global_load_dwordx4 v[4:7], v[62:63], off offset:16
	global_load_dwordx4 v[42:45], v[62:63], off
	s_waitcnt vmcnt(9)
	v_lshlrev_b32_e32 v60, 16, v18
	v_and_b32_e32 v61, 0xffff0000, v18
	v_lshlrev_b32_e32 v18, 16, v19
	v_and_b32_e32 v19, 0xffff0000, v19
	v_pk_add_f32 v[18:19], v[46:47], v[18:19]
	v_pk_add_f32 v[46:47], v[52:53], v[60:61]
	v_lshlrev_b32_e32 v52, 16, v20
	v_and_b32_e32 v53, 0xffff0000, v20
	v_lshlrev_b32_e32 v20, 16, v21
	v_and_b32_e32 v21, 0xffff0000, v21
	v_pk_add_f32 v[20:21], v[48:49], v[20:21]
	v_pk_add_f32 v[48:49], v[50:51], v[52:53]
	s_waitcnt vmcnt(8)
	v_lshlrev_b32_e32 v52, 16, v24
	v_and_b32_e32 v53, 0xffff0000, v24
	v_pk_add_f32 v[16:17], v[16:17], v[52:53]
	v_lshlrev_b32_e32 v50, 16, v22
	v_and_b32_e32 v51, 0xffff0000, v22
	v_lshlrev_b32_e32 v22, 16, v23
	v_and_b32_e32 v23, 0xffff0000, v23
	v_pk_add_f32 v[22:23], v[56:57], v[22:23]
	v_lshlrev_b32_e32 v24, 16, v25
	s_waitcnt vmcnt(7)
	v_lshlrev_b32_e32 v52, 16, v26
	v_and_b32_e32 v53, 0xffff0000, v26
	v_lshlrev_b32_e32 v26, 16, v27
	v_and_b32_e32 v27, 0xffff0000, v27
	v_pk_add_f32 v[18:19], v[18:19], v[26:27]
	v_lshlrev_b32_e32 v26, 16, v28
	v_and_b32_e32 v27, 0xffff0000, v28
	v_lshlrev_b32_e32 v28, 16, v29
	v_and_b32_e32 v29, 0xffff0000, v29
	v_pk_add_f32 v[20:21], v[20:21], v[28:29]
	s_waitcnt vmcnt(6)
	v_lshlrev_b32_e32 v28, 16, v30
	v_and_b32_e32 v29, 0xffff0000, v30
	v_lshlrev_b32_e32 v30, 16, v31
	v_and_b32_e32 v31, 0xffff0000, v31
	v_pk_add_f32 v[22:23], v[22:23], v[30:31]
	v_lshlrev_b32_e32 v30, 16, v32
	v_and_b32_e32 v31, 0xffff0000, v32
	v_pk_add_f32 v[46:47], v[46:47], v[52:53]
	v_pk_add_f32 v[16:17], v[16:17], v[30:31]
	s_waitcnt vmcnt(5)
	v_lshlrev_b32_e32 v30, 16, v34
	v_and_b32_e32 v31, 0xffff0000, v34
	v_and_b32_e32 v25, 0xffff0000, v25
	v_pk_add_f32 v[30:31], v[46:47], v[30:31]
	v_pk_add_f32 v[24:25], v[58:59], v[24:25]
	v_lshlrev_b32_e32 v32, 16, v33
	v_and_b32_e32 v33, 0xffff0000, v33
	v_mul_f32_e32 v30, 0xbfb8aa3b, v30
	v_pk_add_f32 v[24:25], v[24:25], v[32:33]
	v_lshlrev_b32_e32 v32, 16, v35
	v_and_b32_e32 v33, 0xffff0000, v35
	v_exp_f32_e32 v30, v30
	v_pk_add_f32 v[26:27], v[48:49], v[26:27]
	v_pk_add_f32 v[18:19], v[18:19], v[32:33]
	v_lshlrev_b32_e32 v32, 16, v36
	v_and_b32_e32 v33, 0xffff0000, v36
	v_pk_add_f32 v[26:27], v[26:27], v[32:33]
	s_waitcnt vmcnt(4)
	v_lshlrev_b32_e32 v32, 16, v12
	v_and_b32_e32 v33, 0xffff0000, v12
	v_lshlrev_b32_e32 v12, 16, v13
	v_and_b32_e32 v13, 0xffff0000, v13
	v_pk_add_f32 v[22:23], v[22:23], v[12:13]
	v_lshlrev_b32_e32 v12, 16, v14
	v_and_b32_e32 v13, 0xffff0000, v14
	v_lshlrev_b32_e32 v14, 16, v15
	v_and_b32_e32 v15, 0xffff0000, v15
	v_pk_add_f32 v[16:17], v[16:17], v[12:13]
	v_add_f32_e32 v12, 1.0, v30
	v_pk_add_f32 v[24:25], v[24:25], v[14:15]
	v_rcp_f32_e32 v12, v12
	v_mul_f32_e32 v14, 0xbfb8aa3b, v31
	v_exp_f32_e32 v14, v14
	s_waitcnt vmcnt(2)
	v_lshlrev_b32_e32 v13, 16, v38
	v_mul_f32_e32 v12, v12, v13
	s_waitcnt vmcnt(0)
	v_lshlrev_b32_e32 v13, 16, v42
	v_mul_f32_e32 v12, v12, v13
	v_add_f32_e32 v13, 1.0, v14
	v_rcp_f32_e32 v13, v13
	v_mul_f32_e32 v15, 0xbfb8aa3b, v18
	v_exp_f32_e32 v15, v15
	v_and_b32_e32 v14, 0xffff0000, v38
	v_mul_f32_e32 v13, v13, v14
	v_and_b32_e32 v14, 0xffff0000, v42
	v_mul_f32_e32 v13, v13, v14
	v_add_f32_e32 v14, 1.0, v15
	v_mul_f32_e32 v15, 0xbfb8aa3b, v19
	v_rcp_f32_e32 v14, v14
	v_exp_f32_e32 v15, v15
	v_cvt_pk_bf16_f32 v12, v12, v13
	v_lshlrev_b32_e32 v13, 16, v39
	v_mul_f32_e32 v13, v14, v13
	v_add_f32_e32 v14, 1.0, v15
	v_rcp_f32_e32 v14, v14
	v_lshlrev_b32_e32 v15, 16, v43
	v_mul_f32_e32 v13, v13, v15
	v_and_b32_e32 v15, 0xffff0000, v39
	v_mul_f32_e32 v14, v14, v15
	v_mul_f32_e32 v15, 0xbfb8aa3b, v26
	v_exp_f32_e32 v15, v15
	v_and_b32_e32 v18, 0xffff0000, v43
	v_mul_f32_e32 v14, v14, v18
	v_cvt_pk_bf16_f32 v13, v13, v14
	v_add_f32_e32 v14, 1.0, v15
	v_rcp_f32_e32 v14, v14
	v_mul_f32_e32 v18, 0xbfb8aa3b, v27
	v_exp_f32_e32 v18, v18
	v_lshlrev_b32_e32 v15, 16, v40
	v_lshlrev_b32_e32 v34, 16, v37
	v_and_b32_e32 v35, 0xffff0000, v37
	v_mul_f32_e32 v14, v14, v15
	v_lshlrev_b32_e32 v15, 16, v44
	v_pk_add_f32 v[20:21], v[20:21], v[34:35]
	v_mul_f32_e32 v14, v14, v15
	v_add_f32_e32 v15, 1.0, v18
	v_rcp_f32_e32 v15, v15
	v_mul_f32_e32 v19, 0xbfb8aa3b, v20
	v_exp_f32_e32 v19, v19
	v_and_b32_e32 v18, 0xffff0000, v40
	v_mul_f32_e32 v15, v15, v18
	v_and_b32_e32 v18, 0xffff0000, v44
	v_mul_f32_e32 v15, v15, v18
	v_add_f32_e32 v18, 1.0, v19
	v_mul_f32_e32 v19, 0xbfb8aa3b, v21
	v_rcp_f32_e32 v18, v18
	v_exp_f32_e32 v19, v19
	v_cvt_pk_bf16_f32 v14, v14, v15
	v_lshlrev_b32_e32 v15, 16, v41
	v_mul_f32_e32 v15, v18, v15
	v_add_f32_e32 v18, 1.0, v19
	v_rcp_f32_e32 v18, v18
	v_pk_add_f32 v[50:51], v[54:55], v[50:51]
	v_lshlrev_b32_e32 v19, 16, v45
	v_pk_add_f32 v[28:29], v[50:51], v[28:29]
	v_mul_f32_e32 v15, v15, v19
	v_pk_add_f32 v[28:29], v[28:29], v[32:33]
	v_and_b32_e32 v19, 0xffff0000, v41
	v_mul_f32_e32 v18, v18, v19
	v_mul_f32_e32 v19, 0xbfb8aa3b, v28
	v_exp_f32_e32 v19, v19
	v_and_b32_e32 v20, 0xffff0000, v45
	v_mul_f32_e32 v18, v18, v20
	v_cvt_pk_bf16_f32 v15, v15, v18
	v_add_f32_e32 v18, 1.0, v19
	v_rcp_f32_e32 v18, v18
	v_mul_f32_e32 v20, 0xbfb8aa3b, v29
	v_exp_f32_e32 v20, v20
	v_lshlrev_b32_e32 v19, 16, v0
	v_mul_f32_e32 v18, v18, v19
	v_lshlrev_b32_e32 v19, 16, v4
	v_mul_f32_e32 v18, v18, v19
	v_add_f32_e32 v19, 1.0, v20
	v_rcp_f32_e32 v19, v19
	v_mul_f32_e32 v20, 0xbfb8aa3b, v22
	v_exp_f32_e32 v20, v20
	v_and_b32_e32 v0, 0xffff0000, v0
	v_mul_f32_e32 v0, v19, v0
	v_and_b32_e32 v4, 0xffff0000, v4
	v_mul_f32_e32 v0, v0, v4
	v_add_f32_e32 v4, 1.0, v20
	v_mul_f32_e32 v19, 0xbfb8aa3b, v23
	v_rcp_f32_e32 v4, v4
	v_exp_f32_e32 v19, v19
	v_cvt_pk_bf16_f32 v0, v18, v0
	v_lshlrev_b32_e32 v18, 16, v1
	v_mul_f32_e32 v4, v4, v18
	v_add_f32_e32 v18, 1.0, v19
	v_rcp_f32_e32 v18, v18
	v_mul_f32_e32 v16, 0xbfb8aa3b, v16
	v_exp_f32_e32 v16, v16
	v_and_b32_e32 v1, 0xffff0000, v1
	v_lshlrev_b32_e32 v19, 16, v5
	v_mul_f32_e32 v1, v18, v1
	v_and_b32_e32 v5, 0xffff0000, v5
	v_mul_f32_e32 v4, v4, v19
	v_mul_f32_e32 v1, v1, v5
	v_cvt_pk_bf16_f32 v1, v4, v1
	v_add_f32_e32 v4, 1.0, v16
	v_rcp_f32_e32 v4, v4
	v_mul_f32_e32 v16, 0xbfb8aa3b, v17
	v_exp_f32_e32 v16, v16
	v_lshlrev_b32_e32 v5, 16, v2
	v_mul_f32_e32 v4, v4, v5
	v_lshlrev_b32_e32 v5, 16, v6
	v_mul_f32_e32 v4, v4, v5
	v_add_f32_e32 v5, 1.0, v16
	v_rcp_f32_e32 v5, v5
	v_mul_f32_e32 v16, 0xbfb8aa3b, v24
	v_exp_f32_e32 v16, v16
	v_and_b32_e32 v2, 0xffff0000, v2
	v_mul_f32_e32 v2, v5, v2
	v_and_b32_e32 v5, 0xffff0000, v6
	v_mul_f32_e32 v2, v2, v5
	v_add_f32_e32 v5, 1.0, v16
	v_mul_f32_e32 v6, 0xbfb8aa3b, v25
	v_rcp_f32_e32 v5, v5
	v_exp_f32_e32 v6, v6
	v_cvt_pk_bf16_f32 v2, v4, v2
	v_lshlrev_b32_e32 v4, 16, v3
	v_mul_f32_e32 v4, v5, v4
	v_add_f32_e32 v5, 1.0, v6
	v_rcp_f32_e32 v5, v5
	v_and_b32_e32 v3, 0xffff0000, v3
	v_lshlrev_b32_e32 v6, 16, v7
	v_mul_f32_e32 v4, v4, v6
	v_mul_f32_e32 v3, v5, v3
	v_and_b32_e32 v5, 0xffff0000, v7
	v_mul_f32_e32 v3, v3, v5
	v_cvt_pk_bf16_f32 v3, v4, v3
	v_lshlrev_b64 v[4:5], 13, v[8:9]
	v_lshl_add_u64 v[4:5], s[56:57], 0, v[4:5]
	v_lshl_add_u64 v[4:5], v[4:5], 0, v[10:11]
	v_lshl_add_u64 v[6:7], v[4:5], 0, s[4:5]
	v_add_co_u32_e32 v4, vcc, 0x1000, v4
	s_nop 1
	v_addc_co_u32_e32 v5, vcc, 0, v5, vcc
	global_store_dwordx4 v[4:5], v[12:15], off sc1
	global_store_dwordx4 v[6:7], v[0:3], off offset:16 sc1
